# grid barrier: the CU L1 invalidate is issued by wave 1 in parallel with wave 0's arrival/release protocol instead of sitting in wave 0's memory queue
# speedup vs baseline: 1.0209x; 1.0024x over previous
; __device__ __forceinline__ unsigned xb_ld(unsigned* p)              { return __hip_atomic_load(p, __ATOMIC_RELAXED, __HIP_MEMORY_SCOPE_AGENT); }
; __device__ __forceinline__ unsigned xb_add(unsigned* p, unsigned v) { return __hip_atomic_fetch_add(p, v, __ATOMIC_RELAXED, __HIP_MEMORY_SCOPE_AGENT); }
; #define XB_SPIN(cond, bar) do { unsigned _sp = 0; while (cond) { __builtin_amdgcn_s_sleep(1); \
;     if ((++_sp & 255u) == 0u) { if (xb_ld(&(bar)[XB_TMO])) break; if (_sp > XB_SPIN_CAP) { atomicAdd(&(bar)[XB_TMO], 1u); break; } } } } while (0)
; __device__ __forceinline__ void xcd_barrier(const XcdBarrier& b) {
;     ...
;         const unsigned old = xb_add(&bar[XB_XSUB(b.x)], 1u);
;         const unsigned gen = old / nloc;
;         if (old + 1u == (gen + 1u) * nloc) {
;             __builtin_amdgcn_fence(__ATOMIC_RELEASE, "agent");
;             asm volatile("s_waitcnt vmcnt(0)" ::: "memory");
;             const unsigned og = xb_add(&bar[XB_TOP], 1u);
;             const unsigned tg = og / nx;
;             if (og + 1u == (tg + 1u) * nx) xb_add(&bar[XB_TOPGEN], 1u);
;             else XB_SPIN(xb_ld(&bar[XB_TOPGEN]) == tg, bar);
;             __builtin_amdgcn_fence(__ATOMIC_ACQUIRE, "agent");
;             xb_add(&bar[XB_XGEN(b.x)], 1u);
;             asm volatile("s_waitcnt vmcnt(0)" ::: "memory");
;         } else {
;             XB_SPIN(xb_ld(&bar[XB_XGEN(b.x)]) == gen, bar);
.LBB0_40:
	s_or_b64 exec, exec, s[10:11]
	v_cvt_f32_u32_e32 v5, v3
	s_waitcnt vmcnt(0)
	v_readfirstlane_b32 s3, v4
	v_sub_u32_e32 v4, 0, v3
	v_rcp_iflag_f32_e32 v5, v5
	v_add_u32_e32 v6, s3, v2
	v_mul_f32_e32 v5, 0x4f7ffffe, v5
	v_cvt_u32_f32_e32 v5, v5
	v_mul_lo_u32 v2, v4, v5
	v_mul_hi_u32 v2, v5, v2
	v_add_u32_e32 v2, v5, v2
	v_mul_hi_u32 v2, v6, v2
	v_mul_lo_u32 v4, v2, v3
	v_sub_u32_e32 v4, v6, v4
	v_add_u32_e32 v5, 1, v2
	v_sub_u32_e32 v7, v4, v3
	v_cmp_ge_u32_e32 vcc, v4, v3
	s_nop 1
	v_cndmask_b32_e32 v2, v2, v5, vcc
	v_cndmask_b32_e32 v4, v4, v7, vcc
	v_add_u32_e32 v5, 1, v2
	v_cmp_ge_u32_e32 vcc, v4, v3
	v_add_u32_e32 v4, 1, v6
	s_nop 0
	v_cndmask_b32_e32 v2, v2, v5, vcc
	v_mul_lo_u32 v5, v3, v2
	v_add_u32_e32 v3, v5, v3
	v_cmp_ne_u32_e32 vcc, v4, v3
	s_and_saveexec_b64 s[10:11], vcc
	s_xor_b64 s[10:11], exec, s[10:11]
	s_cbranch_execz .LBB0_54
	v_readlane_b32 s14, v252, 14
	v_readlane_b32 s15, v252, 15
	s_waitcnt lgkmcnt(0)
	s_nop 3
	global_load_dword v0, v1, s[14:15] sc1
	s_waitcnt vmcnt(0)
	v_cmp_eq_u32_e32 vcc, v0, v2
	s_and_saveexec_b64 s[16:17], vcc
	s_cbranch_execz .LBB0_53
	s_mov_b32 s3, 1
	s_mov_b64 s[18:19], 0
	s_branch .LBB0_44

; __device__ __forceinline__ unsigned xb_ld(unsigned* p)              { return __hip_atomic_load(p, __ATOMIC_RELAXED, __HIP_MEMORY_SCOPE_AGENT); }
; __device__ __forceinline__ unsigned xb_add(unsigned* p, unsigned v) { return __hip_atomic_fetch_add(p, v, __ATOMIC_RELAXED, __HIP_MEMORY_SCOPE_AGENT); }
; #define XB_SPIN(cond, bar) do { unsigned _sp = 0; while (cond) { __builtin_amdgcn_s_sleep(1); \
;     if ((++_sp & 255u) == 0u) { if (xb_ld(&(bar)[XB_TMO])) break; if (_sp > XB_SPIN_CAP) { atomicAdd(&(bar)[XB_TMO], 1u); break; } } } } while (0)
; __device__ __forceinline__ void xcd_barrier(const XcdBarrier& b) {
;     ...
;     if (threadIdx.x == 0) {
;         unsigned* bar = b.bar;
;         __builtin_amdgcn_s_waitcnt(0);
;         unsigned nloc = b.st[0], nx = b.st[1];
;         if (nloc == 0u) { xcd_barrier_complete(bar, b.x, nloc, nx); b.st[0] = nloc; b.st[1] = nx; }
;         const unsigned old = xb_add(&bar[XB_XSUB(b.x)], 1u);
;         const unsigned gen = old / nloc;
;         if (old + 1u == (gen + 1u) * nloc) {
;             __builtin_amdgcn_fence(__ATOMIC_RELEASE, "agent");
;             asm volatile("s_waitcnt vmcnt(0)" ::: "memory");
;             const unsigned og = xb_add(&bar[XB_TOP], 1u);
;             const unsigned tg = og / nx;
;             if (og + 1u == (tg + 1u) * nx) xb_add(&bar[XB_TOPGEN], 1u);
;             else XB_SPIN(xb_ld(&bar[XB_TOPGEN]) == tg, bar);
;             __builtin_amdgcn_fence(__ATOMIC_ACQUIRE, "agent");
;             xb_add(&bar[XB_XGEN(b.x)], 1u);
;             asm volatile("s_waitcnt vmcnt(0)" ::: "memory");
;         } else {
;             XB_SPIN(xb_ld(&bar[XB_XGEN(b.x)]) == gen, bar);
;             __builtin_amdgcn_fence(__ATOMIC_ACQUIRE, "agent");
;             asm volatile("s_waitcnt vmcnt(0)" ::: "memory");
;         }
;     }
;     __syncthreads();
.LBB0_73:
	s_or_b64 exec, exec, s[16:17]
	s_branch .LBB0_74
.Lxb_other:
	s_mov_b64 exec, s[0:1]
	v_readfirstlane_b32 s3, v187
	s_lshr_b32 s3, s3, 6
	s_cmp_lg_u32 s3, 1
	s_cbranch_scc1 .LBB0_74
	buffer_inv sc1
	s_waitcnt vmcnt(0)
